# P7 row-stat exchange without the panel counter: slots pre-set to -1 in P0, each row thread stores its slot and polls the row's 4 slots with one 16-byte sc1 load (original protocol kept as fallback)
# speedup vs baseline: 1.0043x; 1.0043x over previous
; #define LAS __attribute__((address_space(3)))
; DI void p0_prologue(const Params& P, lds_t* lds, int G, int tid, int wave, int lane, bool late_ffn) {
;     unsigned char* ws = P.ws;
;     LAS float* scr = (LAS float*)(lds + wave * 16384);
;     const int gw = blockIdx.x * 8 + wave, NGW = G * 8;
;     constexpr int I_IN = (DM / 64) * (INW / 32), I_OUT = (DM / 64) * (DM / 32), I_UP = (DM / 64) * (FF / 32), I_DN = (FF / 64) * (DM / 32);
;     const int n_items = late_ffn ? I_IN + I_OUT : I_IN + I_OUT + I_UP + I_DN;
;     for (int it = gw; it < n_items; it += NGW) {
;         int r = it;
;         if (r < I_IN) { p0_transpose_item(P.w_in, DM, INW, (bf16_t*)(ws + WS_WIN), P.norm1, true, scr, r, lane); continue; } r -= I_IN;
.Lxm_ok:
.LBB0_5:
	s_or_b64 exec, exec, s[4:5]
	s_load_dwordx16 s[36:51], s[0:1], 0x0
	v_readlane_b32 s1, v255, 10
	v_mbcnt_lo_u32_b32 v0, -1, 0
	s_and_b32 s97, s1, 0xffffffc0
	v_mbcnt_hi_u32_b32 v201, -1, v0
	s_lshr_b32 s0, s1, 6
	v_add_u32_e32 v175, s97, v201
	s_lshl_b32 s1, s2, 3
	v_mov_b32_e32 v28, v175
	v_writelane_b32 v255, s0, 13
	s_add_i32 s64, s0, s1
	s_lshl_b32 s66, s96, 3
	s_mov_b32 s5, 0
	v_writelane_b32 v255, s1, 14
	s_lshr_b32 s98, s64, 6
	s_lshl_b32 s98, s98, 3
	s_and_b32 s99, s64, 7
	s_or_b32 s98, s98, s99
	s_cmpk_gt_u32 s98, 0x7f
	s_cbranch_scc1 .Lxp_noinit
	s_bfe_u32 s99, s64, 0x30003
	s_lshl_b32 s99, s99, 7
	s_or_b32 s98, s98, s99
	s_lshl_b32 s98, s98, 8
	s_add_u32 s98, s98, 0x180000
	v_lshlrev_b32_e32 v4, 2, v201
	v_add_u32_e32 v4, s98, v4
	v_mov_b32_e32 v5, 0xbf800000
	global_store_dword v4, v5, s[68:69]
.Lxp_noinit:
	s_cmpk_gt_i32 s64, 0x77f
	v_and_b32_e32 v1, 63, v28
	s_cbranch_scc1 .LBB0_32
	s_waitcnt lgkmcnt(0)
	v_and_b32_e32 v123, 7, v201
	v_lshrrev_b32_e32 v122, 3, v201
	v_lshlrev_b32_e32 v124, 5, v122
	s_cmpk_lt_u32 s64, 0x580
	s_cbranch_scc0 .Lp0w_wout
	s_mul_i32 s0, s64, 0x2e9
	s_lshr_b32 s0, s0, 16
	s_mul_i32 s1, s0, 0x58
	s_sub_u32 s1, s64, s1
	s_lshl_b32 s3, s1, 5
	s_mov_b32 s15, 1.0
	s_cmpk_lt_u32 s3, 0x200
	s_cselect_b32 s15, 0x3e000000, s15
	s_sub_u32 s4, s3, 0x500
	s_cmpk_lt_u32 s4, 0x200
	s_cselect_b32 s15, 0x3db504f3, s15
	s_and_b32 s17, s3, 0xff
	s_lshr_b32 s18, s17, 7
	s_lshl_b32 s18, s18, 7
	s_bfe_u32 s19, s17, 0x10005
	s_lshl_b32 s19, s19, 6
	s_add_u32 s18, s18, s19
	s_bfe_u32 s19, s17, 0x10006
	s_lshl_b32 s19, s19, 5
	s_add_u32 s18, s18, s19
	s_andn2_b32 s19, s3, 0xff
	s_add_u32 s18, s18, s19
	s_sub_u32 s4, s3, 0x300
	s_cmpk_lt_u32 s4, 0x400
	s_cselect_b32 s3, s18, s3
	s_mul_i32 s4, s0, 0xb0000
	s_lshl_b32 s17, s1, 7
	s_add_u32 s4, s4, s17
	s_add_u32 s6, s48, s4
	s_addc_u32 s7, s49, 0
	s_lshl_b32 s4, s3, 11
	s_lshl_b32 s17, s0, 7
	s_add_u32 s4, s4, s17
	s_add_u32 s4, s4, 0x200000
	s_add_u32 s8, s68, s4
	s_addc_u32 s9, s69, 0
	s_movk_i32 s12, 0x2c00
	s_mov_b32 s14, 1
	s_branch .Lp0w_common

;     __device__ __forceinline__ void fused(f32x4 (&acc)[2][2][4][2], const Unit& u, int wr, int wc, int fr, int fq, PG8_LAS unsigned char* lds, int wid, int lane) const {
;     ...
;         if (tid < 256) {
;             const float t = (Pp[tid * 4] + Pp[tid * 4 + 1]) + (Pp[tid * 4 + 2] + Pp[tid * 4 + 3]);
;             __hip_atomic_store(xbuf + ((size_t)(u.pm * BM + tid) * 4 + u.pn), t, __ATOMIC_RELAXED, __HIP_MEMORY_SCOPE_AGENT);
;         }
;         asm volatile("s_waitcnt vmcnt(0)" ::: "memory");
;         __builtin_amdgcn_s_barrier(); asm volatile("" ::: "memory");
;         if (tid == 0) {
;             unsigned* cw = cnt + 64 * u.pm;
;             __hip_atomic_fetch_add(cw, 1u, __ATOMIC_RELAXED, __HIP_MEMORY_SCOPE_AGENT);
;             unsigned sp = 0;
;             while (__hip_atomic_load(cw, __ATOMIC_RELAXED, __HIP_MEMORY_SCOPE_AGENT) < 4u) { __builtin_amdgcn_s_sleep(2); if (++sp > (1u << 20)) break; }
;             __builtin_amdgcn_fence(__ATOMIC_ACQUIRE, "agent");
;         }
;         asm volatile("s_waitcnt vmcnt(0) lgkmcnt(0)" ::: "memory"); __builtin_amdgcn_s_barrier(); asm volatile("" ::: "memory");
.LBB0_1082:
	s_or_b64 exec, exec, s[8:9]
	s_cmp_lg_u32 s100, 0
	s_cbranch_scc1 .Lxp_orig
	s_and_saveexec_b64 s[8:9], s[0:1]
	s_cbranch_execz .LBB0_1101
	v_lshl_add_u64 v[0:1], v[0:1], 4, s[4:5]
	s_waitcnt vmcnt(0)
	s_mov_b32 s14, 0x40000
.Lxp_poll:
	global_load_dwordx4 v[8:11], v[0:1], off sc1
	s_waitcnt vmcnt(0)
	v_min_f32_e32 v3, v8, v9
	v_min3_f32 v3, v3, v10, v11
	v_cmp_gt_f32_e32 vcc, 0, v3
	s_cbranch_vccz .Lxp_done
	s_sleep 1
	s_sub_u32 s14, s14, 1
	s_cmp_eq_u32 s14, 0
	s_cbranch_scc0 .Lxp_poll
.Lxp_done:
	v_mov_b32_e32 v4, v8
	v_mov_b32_e32 v6, v9
	v_mov_b32_e32 v5, v10
	v_mov_b32_e32 v7, v11
	v_mov_b32_e32 v3, 0x358637bd
	s_mov_b32 s0, 0x800000
	s_branch .Lxp_join
.Lxp_orig:
	s_waitcnt vmcnt(0)
	s_barrier
	v_cmp_eq_u32_e32 vcc, 0, v2
	s_and_saveexec_b64 s[8:9], vcc
	s_cbranch_execz .LBB0_1099
	s_lshl_b32 s10, s12, 6
	s_ashr_i32 s11, s10, 31
	s_lshl_b64 s[10:11], s[10:11], 2
	s_mov_b64 s[14:15], exec
	s_add_u32 s10, s68, s10
	s_addc_u32 s11, s69, s11
	v_mbcnt_lo_u32_b32 v3, s14, 0
	s_add_u32 s10, s10, 0x40000
	v_mbcnt_hi_u32_b32 v3, s15, v3
	s_addc_u32 s11, s11, 0
	v_cmp_eq_u32_e32 vcc, 0, v3
	s_and_saveexec_b64 s[12:13], vcc
	s_cbranch_execz .LBB0_1085
	s_bcnt1_i32_b64 s14, s[14:15]
	v_mov_b32_e32 v3, 0
	v_mov_b32_e32 v4, s14
	global_atomic_add v3, v4, s[10:11]

;     __device__ __forceinline__ void fused(f32x4 (&acc)[2][2][4][2], const Unit& u, int wr, int wc, int fr, int fq, PG8_LAS unsigned char* lds, int wid, int lane) const {
;     ...
;         if (tid < 256) {
;             const float* slot = xbuf + (size_t)(u.pm * BM + tid) * 4;
;             const float t = (__hip_atomic_load(slot, __ATOMIC_RELAXED, __HIP_MEMORY_SCOPE_AGENT) + __hip_atomic_load(slot + 1, __ATOMIC_RELAXED, __HIP_MEMORY_SCOPE_AGENT))
;                           + (__hip_atomic_load(slot + 2, __ATOMIC_RELAXED, __HIP_MEMORY_SCOPE_AGENT) + __hip_atomic_load(slot + 3, __ATOMIC_RELAXED, __HIP_MEMORY_SCOPE_AGENT));
;             Sr[tid] = rsqrtf(t * (1.0f / DM) + EPS);
;         }
.Lxp_join:
	v_pk_add_f32 v[0:1], v[4:5], v[6:7]
	s_nop 0
	v_add_f32_e32 v0, v0, v1
	v_fmac_f32_e32 v3, 0x3a800000, v0
	v_mul_f32_e32 v0, 0x4b800000, v3
	v_cmp_gt_f32_e32 vcc, s0, v3
	v_lshl_add_u32 v1, v2, 2, 0
	v_add_u32_e32 v1, 0x21400, v1
	v_cndmask_b32_e32 v0, v3, v0, vcc
	v_rsq_f32_e32 v0, v0
	s_nop 0
	v_mul_f32_e32 v2, 0x45800000, v0
	v_cndmask_b32_e32 v0, v0, v2, vcc
	ds_write_b32 v1, v0
